# strategy #7 (DPP instead of LDS round trips): v38 + P0 RMSNorm loop wave-wide all-reduces (rstd sum and the 5 forget-logit dots) via v_add_f32_dpp / v_permlane16/32_swap instead of 36 ds_bpermute roun
# speedup vs baseline: 1.0036x; 1.0010x over previous
.LBB0_78:
	s_waitcnt lgkmcnt(0)
	v_pk_mul_f32 v[86:87], v[4:5], v[4:5]
	v_pk_mul_f32 v[88:89], v[8:9], v[8:9]
	v_pk_mul_f32 v[90:91], v[6:7], v[6:7]
	v_pk_mul_f32 v[92:93], v[2:3], v[2:3]
	v_pk_mul_f32 v[82:83], v[12:13], v[12:13]
	v_pk_mul_f32 v[84:85], v[10:11], v[10:11]
	v_mov_b32_e32 v98, v92
	v_mov_b32_e32 v99, v90
	v_mov_b32_e32 v90, v93
	v_mov_b32_e32 v92, v86
	v_mov_b32_e32 v93, v88
	v_mov_b32_e32 v88, v87
	v_pk_add_f32 v[90:91], v[98:99], v[90:91]
	v_pk_add_f32 v[86:87], v[92:93], v[88:89]
	v_pk_mov_b32 v[88:89], v[84:85], v[82:83] op_sel:[1,0]
	v_mov_b32_e32 v85, v83
	v_mul_f32_e32 v34, v14, v14
	v_pk_add_f32 v[86:87], v[90:91], v[86:87]
	v_pk_add_f32 v[82:83], v[88:89], v[84:85]
	v_pk_fma_f32 v[84:85], v[14:15], v[14:15], v[34:35] op_sel_hi:[1,1,0]
	v_mul_f32_e32 v34, v16, v16
	v_pk_add_f32 v[86:87], v[86:87], v[86:87] op_sel_hi:[0,1]
	v_pk_add_f32 v[82:83], v[82:83], v[82:83] op_sel_hi:[0,1]
	v_pk_fma_f32 v[88:89], v[16:17], v[16:17], v[34:35] op_sel_hi:[1,1,0]
	v_mul_f32_e32 v84, v18, v18
	v_mul_f32_e32 v88, v19, v19
	v_mul_f32_e32 v82, v20, v20
	v_mul_f32_e32 v86, v21, v21
	v_pk_mul_f32 v[78:79], v[24:25], v[24:25]
	v_pk_mul_f32 v[80:81], v[22:23], v[22:23]
	v_pk_add_f32 v[84:85], v[84:85], v[88:89]
	v_pk_add_f32 v[82:83], v[82:83], v[86:87]
	v_mul_f32_e32 v34, v26, v26
	v_pk_add_f32 v[82:83], v[84:85], v[82:83]
	v_pk_mov_b32 v[84:85], v[80:81], v[78:79] op_sel:[1,0]
	v_mov_b32_e32 v81, v79
	v_pk_add_f32 v[78:79], v[84:85], v[80:81]
	v_pk_fma_f32 v[80:81], v[26:27], v[26:27], v[34:35] op_sel_hi:[1,1,0]
	v_mul_f32_e32 v34, v28, v28
	v_pk_add_f32 v[82:83], v[82:83], v[82:83] op_sel_hi:[0,1]
	v_pk_add_f32 v[78:79], v[78:79], v[78:79] op_sel_hi:[0,1]
	v_pk_fma_f32 v[84:85], v[28:29], v[28:29], v[34:35] op_sel_hi:[1,1,0]
	v_mul_f32_e32 v80, v30, v30
	v_mul_f32_e32 v84, v31, v31
	v_mul_f32_e32 v78, v32, v32
	v_mul_f32_e32 v82, v33, v33
	v_pk_add_f32 v[80:81], v[80:81], v[84:85]
	v_pk_add_f32 v[78:79], v[78:79], v[82:83]
	s_mov_b32 s8, 0xf800000
	v_pk_add_f32 v[78:79], v[80:81], v[78:79]
	s_nop 0
	v_add_f32_e32 v34, v78, v79
	s_nop 1
	v_add_f32_dpp v34, v34, v34 quad_perm:[1,0,3,2] row_mask:0xf bank_mask:0xf
	s_nop 1
	v_add_f32_dpp v34, v34, v34 quad_perm:[2,3,0,1] row_mask:0xf bank_mask:0xf
	s_nop 1
	v_add_f32_dpp v34, v34, v34 row_half_mirror row_mask:0xf bank_mask:0xf
	s_nop 1
	v_add_f32_dpp v34, v34, v34 row_mirror row_mask:0xf bank_mask:0xf
	v_mov_b32_e32 v71, v34
	s_nop 1
	v_permlane16_swap_b32_e32 v71, v34
	v_add_f32_e32 v34, v34, v71
	v_mov_b32_e32 v71, v34
	s_nop 1
	v_permlane32_swap_b32_e32 v71, v34
	v_add_f32_e32 v34, v34, v71
	v_fmamk_f32 v34, v34, 0x3a000000, v214
	v_mul_f32_e32 v71, 0x4f800000, v34
	v_cmp_gt_f32_e32 vcc, s8, v34
	s_nop 1
	v_cndmask_b32_e32 v34, v34, v71, vcc
	v_sqrt_f32_e32 v71, v34
	s_nop 0
	v_add_u32_e32 v78, -1, v71
	v_fma_f32 v79, -v78, v71, v34
	v_cmp_ge_f32_e64 s[50:51], 0, v79
	v_add_u32_e32 v79, 1, v71
	s_nop 0
	v_cndmask_b32_e64 v78, v71, v78, s[50:51]
	v_fma_f32 v71, -v79, v71, v34
	v_cmp_lt_f32_e64 s[50:51], 0, v71
	s_nop 1
	v_cndmask_b32_e64 v71, v78, v79, s[50:51]
	v_mul_f32_e32 v78, 0x37800000, v71
	v_cndmask_b32_e32 v71, v71, v78, vcc
	v_cmp_class_f32_e32 vcc, v34, v215
	s_nop 1
	v_cndmask_b32_e32 v34, v71, v34, vcc
	v_div_scale_f32 v71, s[8:9], v34, v34, 1.0
	v_rcp_f32_e32 v78, v71
	s_nop 0
	v_fma_f32 v79, -v71, v78, 1.0
	v_fmac_f32_e32 v78, v79, v78
	v_div_scale_f32 v79, vcc, 1.0, v34, 1.0
	v_mul_f32_e32 v80, v79, v78
	v_fma_f32 v81, -v71, v80, v79
	v_fmac_f32_e32 v80, v81, v78
	v_fma_f32 v71, -v71, v80, v79
	v_div_fmas_f32 v71, v71, v78, v80
	v_div_fixup_f32 v34, v71, v34, 1.0
	s_and_saveexec_b64 s[8:9], s[38:39]
	s_cbranch_execz .LBB0_80
	s_lshl_b64 s[10:11], s[4:5], 2
	s_add_u32 s10, s76, s10
	s_addc_u32 s11, s77, s11
	global_store_dword v35, v34, s[10:11]
.LBB0_80:
	s_or_b64 exec, exec, s[8:9]
	v_pk_mul_f32 v[2:3], v[2:3], v[34:35] op_sel_hi:[1,0]
	v_pk_mul_f32 v[4:5], v[4:5], v[34:35] op_sel_hi:[1,0]
	s_waitcnt vmcnt(0)
	v_pk_mul_f32 v[92:93], v[36:37], v[2:3]
	v_pk_mul_f32 v[2:3], v[6:7], v[34:35] op_sel_hi:[1,0]
	v_pk_mul_f32 v[88:89], v[38:39], v[4:5]
	v_pk_mul_f32 v[4:5], v[8:9], v[34:35] op_sel_hi:[1,0]
	s_waitcnt vmcnt(6)
	v_pk_mul_f32 v[90:91], v[40:41], v[2:3]
	v_pk_mul_f32 v[2:3], v[10:11], v[34:35] op_sel_hi:[1,0]
	v_pk_mul_f32 v[86:87], v[42:43], v[4:5]
	v_pk_mul_f32 v[4:5], v[12:13], v[34:35] op_sel_hi:[1,0]
	s_waitcnt vmcnt(5)
	v_pk_mul_f32 v[84:85], v[44:45], v[2:3]
	v_pk_mul_f32 v[2:3], v[14:15], v[34:35] op_sel_hi:[1,0]
	v_pk_mul_f32 v[80:81], v[46:47], v[4:5]
	v_pk_mul_f32 v[4:5], v[16:17], v[34:35] op_sel_hi:[1,0]
	s_waitcnt vmcnt(4)
	v_pk_mul_f32 v[82:83], v[48:49], v[2:3]
	v_pk_mul_f32 v[2:3], v[18:19], v[34:35] op_sel_hi:[1,0]
	v_add_u32_e32 v18, 0, v70
	v_pk_mul_f32 v[78:79], v[50:51], v[4:5]
	v_pk_mul_f32 v[4:5], v[20:21], v[34:35] op_sel_hi:[1,0]
	s_waitcnt vmcnt(3)
	v_pk_mul_f32 v[16:17], v[52:53], v[2:3]
	v_pk_mul_f32 v[2:3], v[22:23], v[34:35] op_sel_hi:[1,0]
	ds_read_b128 v[20:23], v18
	v_pk_mul_f32 v[12:13], v[54:55], v[4:5]
	v_pk_mul_f32 v[4:5], v[24:25], v[34:35] op_sel_hi:[1,0]
	s_waitcnt vmcnt(2)
	v_pk_mul_f32 v[14:15], v[56:57], v[2:3]
	v_pk_mul_f32 v[8:9], v[58:59], v[4:5]
	v_pk_mul_f32 v[4:5], v[26:27], v[34:35] op_sel_hi:[1,0]
	ds_read_b128 v[24:27], v18 offset:1024
	s_waitcnt lgkmcnt(1)
	v_mul_f32_e32 v19, v93, v21
	v_fmac_f32_e32 v19, v92, v20
	v_mul_f32_e32 v20, v89, v23
	v_fmac_f32_e32 v20, v88, v22
	s_waitcnt lgkmcnt(0)
	v_mul_f32_e32 v25, v91, v25
	v_add_f32_e32 v19, v19, v20
	v_fmac_f32_e32 v25, v90, v24
	v_mul_f32_e32 v24, v87, v27
	ds_read_b128 v[20:23], v18 offset:2048
	v_fmac_f32_e32 v24, v86, v26
	v_add_f32_e32 v19, 0, v19
	v_add_f32_e32 v24, v25, v24
	v_add_f32_e32 v19, v19, v24
	ds_read_b128 v[24:27], v18 offset:3072
	s_waitcnt lgkmcnt(1)
	v_mul_f32_e32 v21, v85, v21
	v_fmac_f32_e32 v21, v84, v20
	v_mul_f32_e32 v20, v81, v23
	v_fmac_f32_e32 v20, v80, v22
	v_add_f32_e32 v20, v21, v20
	s_waitcnt lgkmcnt(0)
	v_mul_f32_e32 v25, v83, v25
	v_add_f32_e32 v19, v19, v20
	v_fmac_f32_e32 v25, v82, v24
	v_mul_f32_e32 v24, v79, v27
	ds_read_b128 v[20:23], v18 offset:4096
	v_fmac_f32_e32 v24, v78, v26
	v_add_f32_e32 v24, v25, v24
	v_add_f32_e32 v19, v19, v24
	ds_read_b128 v[24:27], v18 offset:5120
	s_waitcnt lgkmcnt(1)
	v_mul_f32_e32 v21, v17, v21
	v_fmac_f32_e32 v21, v16, v20
	v_mul_f32_e32 v20, v13, v23
	v_fmac_f32_e32 v20, v12, v22
	v_add_f32_e32 v20, v21, v20
	s_waitcnt lgkmcnt(0)
	v_mul_f32_e32 v25, v15, v25
	v_add_f32_e32 v19, v19, v20
	v_fmac_f32_e32 v25, v14, v24
	v_mul_f32_e32 v24, v9, v27
	ds_read_b128 v[20:23], v18 offset:6144
	v_fmac_f32_e32 v24, v8, v26
	v_add_f32_e32 v24, v25, v24
	v_add_f32_e32 v19, v19, v24
	ds_read_b128 v[24:27], v18 offset:7168
	v_pk_mul_f32 v[2:3], v[28:29], v[34:35] op_sel_hi:[1,0]
	s_waitcnt vmcnt(1)
	v_pk_mul_f32 v[4:5], v[60:61], v[4:5]
	v_pk_mul_f32 v[2:3], v[62:63], v[2:3]
	s_waitcnt lgkmcnt(1)
	v_mul_f32_e32 v21, v5, v21
	v_pk_mul_f32 v[10:11], v[30:31], v[34:35] op_sel_hi:[1,0]
	v_fmac_f32_e32 v21, v4, v20
	v_mul_f32_e32 v20, v3, v23
	v_pk_mul_f32 v[6:7], v[32:33], v[34:35] op_sel_hi:[1,0]
	s_waitcnt vmcnt(0)
	v_pk_mul_f32 v[10:11], v[64:65], v[10:11]
	v_fmac_f32_e32 v20, v2, v22
	v_pk_mul_f32 v[6:7], v[66:67], v[6:7]
	v_add_f32_e32 v20, v21, v20
	s_waitcnt lgkmcnt(0)
	v_mul_f32_e32 v25, v11, v25
	v_add_f32_e32 v19, v19, v20
	v_fmac_f32_e32 v25, v10, v24
	v_mul_f32_e32 v24, v7, v27
	ds_read_b128 v[20:23], v18 offset:8192
	v_fmac_f32_e32 v24, v6, v26
	v_add_f32_e32 v24, v25, v24
	v_add_f32_e32 v19, v19, v24
	ds_read_b128 v[24:27], v18 offset:9216
	s_waitcnt lgkmcnt(1)
	v_mul_f32_e32 v21, v93, v21
	v_fmac_f32_e32 v21, v92, v20
	v_mul_f32_e32 v20, v89, v23
	v_fmac_f32_e32 v20, v88, v22
	v_add_f32_e32 v20, v21, v20
	s_waitcnt lgkmcnt(0)
	v_mul_f32_e32 v25, v91, v25
	v_add_f32_e32 v29, 0, v20
	v_fmac_f32_e32 v25, v90, v24
	v_mul_f32_e32 v24, v87, v27
	ds_read_b128 v[20:23], v18 offset:10240
	v_fmac_f32_e32 v24, v86, v26
	v_add_f32_e32 v24, v25, v24
	v_add_f32_e32 v29, v29, v24
	ds_read_b128 v[24:27], v18 offset:11264
	s_waitcnt lgkmcnt(1)
	v_mul_f32_e32 v21, v85, v21
	v_fmac_f32_e32 v21, v84, v20
	v_mul_f32_e32 v20, v81, v23
	v_fmac_f32_e32 v20, v80, v22
	v_add_f32_e32 v20, v21, v20
	s_waitcnt lgkmcnt(0)
	v_mul_f32_e32 v25, v83, v25
	v_add_f32_e32 v29, v29, v20
	v_fmac_f32_e32 v25, v82, v24
	v_mul_f32_e32 v24, v79, v27
	ds_read_b128 v[20:23], v18 offset:12288
	v_fmac_f32_e32 v24, v78, v26
	v_add_f32_e32 v24, v25, v24
	v_add_f32_e32 v29, v29, v24
	ds_read_b128 v[24:27], v18 offset:13312
	s_waitcnt lgkmcnt(1)
	v_mul_f32_e32 v21, v17, v21
	v_fmac_f32_e32 v21, v16, v20
	v_mul_f32_e32 v20, v13, v23
	v_fmac_f32_e32 v20, v12, v22
	v_add_f32_e32 v20, v21, v20
	s_waitcnt lgkmcnt(0)
	v_mul_f32_e32 v25, v15, v25
	v_add_f32_e32 v29, v29, v20
	v_fmac_f32_e32 v25, v14, v24
	v_mul_f32_e32 v24, v9, v27
	ds_read_b128 v[20:23], v18 offset:14336
	v_fmac_f32_e32 v24, v8, v26
	v_add_f32_e32 v24, v25, v24
	v_add_f32_e32 v29, v29, v24
	ds_read_b128 v[24:27], v18 offset:15360
	s_waitcnt lgkmcnt(1)
	v_mul_f32_e32 v21, v5, v21
	v_fmac_f32_e32 v21, v4, v20
	v_mul_f32_e32 v20, v3, v23
	v_fmac_f32_e32 v20, v2, v22
	v_add_f32_e32 v20, v21, v20
	s_waitcnt lgkmcnt(0)
	v_mul_f32_e32 v21, v11, v25
	v_mul_f32_e32 v22, v7, v27
	v_fmac_f32_e32 v21, v10, v24
	v_fmac_f32_e32 v22, v6, v26
	v_add_f32_e32 v20, v29, v20
	v_add_f32_e32 v21, v21, v22
	v_add_f32_e32 v20, v20, v21
	ds_read_b128 v[24:27], v18 offset:16384
	s_waitcnt lgkmcnt(1)
	s_nop 1
	v_add_f32_dpp v20, v20, v20 quad_perm:[1,0,3,2] row_mask:0xf bank_mask:0xf
	s_waitcnt lgkmcnt(1)
	s_nop 1
	v_add_f32_dpp v19, v19, v19 quad_perm:[1,0,3,2] row_mask:0xf bank_mask:0xf
	ds_read_b128 v[28:31], v18 offset:17408
	s_waitcnt lgkmcnt(1)
	s_nop 1
	v_add_f32_dpp v20, v20, v20 quad_perm:[2,3,0,1] row_mask:0xf bank_mask:0xf
	s_waitcnt lgkmcnt(0)
	v_mul_f32_e32 v29, v91, v29
	v_fmac_f32_e32 v29, v90, v28
	v_mul_f32_e32 v28, v87, v31
	v_fmac_f32_e32 v28, v86, v30
	s_nop 1
	v_add_f32_dpp v20, v20, v20 row_half_mirror row_mask:0xf bank_mask:0xf
	v_add_f32_e32 v28, v29, v28
	s_nop 1
	v_add_f32_dpp v19, v19, v19 quad_perm:[2,3,0,1] row_mask:0xf bank_mask:0xf
	s_nop 1
	v_add_f32_dpp v21, v20, v20 row_mirror row_mask:0xf bank_mask:0xf
	v_mov_b32_e32 v23, v21
	s_nop 1
	v_permlane16_swap_b32_e32 v23, v21
	s_nop 1
	v_add_f32_dpp v19, v19, v19 row_half_mirror row_mask:0xf bank_mask:0xf
	v_add_f32_e32 v21, v21, v23
	v_mul_f32_e32 v23, v93, v25
	v_fmac_f32_e32 v23, v92, v24
	v_mul_f32_e32 v24, v89, v27
	v_fmac_f32_e32 v24, v88, v26
	v_add_f32_e32 v23, v23, v24
	ds_read_b128 v[24:27], v18 offset:18432
	v_add_f32_e32 v23, 0, v23
	v_add_f32_e32 v23, v23, v28
	ds_read_b128 v[28:31], v18 offset:19456
	s_waitcnt lgkmcnt(2)
	s_nop 1
	v_add_f32_dpp v19, v19, v19 row_mirror row_mask:0xf bank_mask:0xf
	s_waitcnt lgkmcnt(1)
	v_mul_f32_e32 v25, v85, v25
	v_fmac_f32_e32 v25, v84, v24
	v_mul_f32_e32 v24, v81, v27
	v_fmac_f32_e32 v24, v80, v26
	s_waitcnt lgkmcnt(0)
	v_mul_f32_e32 v29, v83, v29
	v_add_f32_e32 v24, v25, v24
	v_fmac_f32_e32 v29, v82, v28
	v_mul_f32_e32 v28, v79, v31
	v_add_f32_e32 v23, v23, v24
	ds_read_b128 v[24:27], v18 offset:20480
	v_fmac_f32_e32 v28, v78, v30
	v_add_f32_e32 v28, v29, v28
	v_add_f32_e32 v23, v23, v28
	ds_read_b128 v[28:31], v18 offset:21504
	s_waitcnt lgkmcnt(1)
	v_mul_f32_e32 v25, v17, v25
	v_fmac_f32_e32 v25, v16, v24
	v_mul_f32_e32 v24, v13, v27
	v_fmac_f32_e32 v24, v12, v26
	s_waitcnt lgkmcnt(0)
	v_mul_f32_e32 v29, v15, v29
	v_add_f32_e32 v24, v25, v24
	v_fmac_f32_e32 v29, v14, v28
	v_mul_f32_e32 v28, v9, v31
	v_add_f32_e32 v23, v23, v24
	ds_read_b128 v[24:27], v18 offset:22528
	v_fmac_f32_e32 v28, v8, v30
	v_add_f32_e32 v28, v29, v28
	v_add_f32_e32 v23, v23, v28
	ds_read_b128 v[28:31], v18 offset:23552
	s_waitcnt lgkmcnt(1)
	v_mul_f32_e32 v25, v5, v25
	v_fmac_f32_e32 v25, v4, v24
	v_mul_f32_e32 v24, v3, v27
	v_fmac_f32_e32 v24, v2, v26
	s_waitcnt lgkmcnt(0)
	v_mul_f32_e32 v29, v11, v29
	v_add_f32_e32 v24, v25, v24
	v_fmac_f32_e32 v29, v10, v28
	v_mul_f32_e32 v28, v7, v31
	v_add_f32_e32 v23, v23, v24
	v_fmac_f32_e32 v28, v6, v30
	ds_read_b128 v[24:27], v18 offset:24576
	v_add_f32_e32 v28, v29, v28
	v_add_f32_e32 v23, v23, v28
	ds_read_b128 v[28:31], v18 offset:25600
	s_waitcnt lgkmcnt(1)
	v_mul_f32_e32 v25, v93, v25
	v_fmac_f32_e32 v25, v92, v24
	v_mul_f32_e32 v24, v89, v27
	v_fmac_f32_e32 v24, v88, v26
	s_waitcnt lgkmcnt(0)
	v_mul_f32_e32 v29, v91, v29
	v_add_f32_e32 v24, v25, v24
	v_fmac_f32_e32 v29, v90, v28
	v_mul_f32_e32 v28, v87, v31
	v_add_f32_e32 v33, 0, v24
	ds_read_b128 v[24:27], v18 offset:26624
	v_fmac_f32_e32 v28, v86, v30
	v_add_f32_e32 v28, v29, v28
	v_add_f32_e32 v33, v33, v28
	ds_read_b128 v[28:31], v18 offset:27648
	s_waitcnt lgkmcnt(1)
	v_mul_f32_e32 v25, v85, v25
	v_fmac_f32_e32 v25, v84, v24
	v_mul_f32_e32 v24, v81, v27
	v_fmac_f32_e32 v24, v80, v26
	s_waitcnt lgkmcnt(0)
	v_mul_f32_e32 v29, v83, v29
	v_add_f32_e32 v24, v25, v24
	v_fmac_f32_e32 v29, v82, v28
	v_mul_f32_e32 v28, v79, v31
	v_add_f32_e32 v33, v33, v24
	ds_read_b128 v[24:27], v18 offset:28672
	v_fmac_f32_e32 v28, v78, v30
	v_add_f32_e32 v28, v29, v28
	v_add_f32_e32 v33, v33, v28
	ds_read_b128 v[28:31], v18 offset:29696
	s_waitcnt lgkmcnt(1)
	v_mul_f32_e32 v25, v17, v25
	v_fmac_f32_e32 v25, v16, v24
	v_mul_f32_e32 v24, v13, v27
	v_fmac_f32_e32 v24, v12, v26
	s_waitcnt lgkmcnt(0)
	v_mul_f32_e32 v29, v15, v29
	v_add_f32_e32 v24, v25, v24
	v_fmac_f32_e32 v29, v14, v28
	v_mul_f32_e32 v28, v9, v31
	v_add_f32_e32 v33, v33, v24
	ds_read_b128 v[24:27], v18 offset:30720
	v_fmac_f32_e32 v28, v8, v30
	v_add_f32_e32 v28, v29, v28
	v_add_f32_e32 v33, v33, v28
	ds_read_b128 v[28:31], v18 offset:31744
	s_waitcnt lgkmcnt(1)
	v_mul_f32_e32 v25, v5, v25
	v_fmac_f32_e32 v25, v4, v24
	v_mul_f32_e32 v24, v3, v27
	v_fmac_f32_e32 v24, v2, v26
	s_waitcnt lgkmcnt(0)
	v_mul_f32_e32 v29, v11, v29
	v_add_f32_e32 v24, v25, v24
	v_fmac_f32_e32 v29, v10, v28
	v_mul_f32_e32 v28, v7, v31
	v_add_f32_e32 v33, v33, v24
	v_fmac_f32_e32 v28, v6, v30
	ds_read_b128 v[24:27], v18 offset:32768
	v_add_f32_e32 v28, v29, v28
	v_add_f32_e32 v33, v33, v28
	ds_read_b128 v[28:31], v18 offset:33792
	s_waitcnt lgkmcnt(1)
	v_mul_f32_e32 v25, v93, v25
	v_fmac_f32_e32 v25, v92, v24
	v_mul_f32_e32 v24, v89, v27
	v_fmac_f32_e32 v24, v88, v26
	s_waitcnt lgkmcnt(0)
	v_mul_f32_e32 v29, v91, v29
	v_add_f32_e32 v24, v25, v24
	v_fmac_f32_e32 v29, v90, v28
	v_mul_f32_e32 v28, v87, v31
	v_add_f32_e32 v71, 0, v24
	ds_read_b128 v[24:27], v18 offset:34816
	v_fmac_f32_e32 v28, v86, v30
	v_add_f32_e32 v28, v29, v28
	v_add_f32_e32 v71, v71, v28
	ds_read_b128 v[28:31], v18 offset:35840
	s_waitcnt lgkmcnt(1)
	v_mul_f32_e32 v25, v85, v25
	v_fmac_f32_e32 v25, v84, v24
	v_mul_f32_e32 v24, v81, v27
	v_fmac_f32_e32 v24, v80, v26
	s_waitcnt lgkmcnt(0)
	v_mul_f32_e32 v29, v83, v29
	v_add_f32_e32 v24, v25, v24
	v_fmac_f32_e32 v29, v82, v28
	v_mul_f32_e32 v28, v79, v31
	v_add_f32_e32 v71, v71, v24
	ds_read_b128 v[24:27], v18 offset:36864
	v_fmac_f32_e32 v28, v78, v30
	v_add_f32_e32 v28, v29, v28
	v_add_f32_e32 v71, v71, v28
	ds_read_b128 v[28:31], v18 offset:37888
	s_waitcnt lgkmcnt(1)
	v_mul_f32_e32 v17, v17, v25
	v_mul_f32_e32 v13, v13, v27
	v_fmac_f32_e32 v17, v16, v24
	v_fmac_f32_e32 v13, v12, v26
	v_add_f32_e32 v12, v17, v13
	s_waitcnt lgkmcnt(0)
	v_mul_f32_e32 v17, v15, v29
	v_add_f32_e32 v16, v71, v12
	v_fmac_f32_e32 v17, v14, v28
	ds_read_b128 v[12:15], v18 offset:38912
	ds_read_b128 v[24:27], v18 offset:39936
	v_mul_f32_e32 v9, v9, v31
	v_fmac_f32_e32 v9, v8, v30
	v_add_f32_e32 v8, v17, v9
	s_waitcnt lgkmcnt(1)
	v_mul_f32_e32 v5, v5, v13
	v_mul_f32_e32 v3, v3, v15
	v_fmac_f32_e32 v5, v4, v12
	v_fmac_f32_e32 v3, v2, v14
	v_add_f32_e32 v2, v5, v3
	s_waitcnt lgkmcnt(0)
	v_mul_f32_e32 v3, v11, v25
	v_mul_f32_e32 v4, v7, v27
	v_add_f32_e32 v8, v16, v8
	v_fmac_f32_e32 v3, v10, v24
	v_fmac_f32_e32 v4, v6, v26
	v_add_f32_e32 v2, v8, v2
	v_add_f32_e32 v3, v3, v4
	v_add_f32_e32 v2, v2, v3
	s_nop 1
	v_add_f32_dpp v4, v23, v23 quad_perm:[1,0,3,2] row_mask:0xf bank_mask:0xf
	s_nop 1
	v_add_f32_dpp v6, v33, v33 quad_perm:[1,0,3,2] row_mask:0xf bank_mask:0xf
	s_nop 1
	v_add_f32_dpp v2, v2, v2 quad_perm:[1,0,3,2] row_mask:0xf bank_mask:0xf
	v_mov_b32_e32 v22, v19
	s_nop 1
	v_permlane16_swap_b32_e32 v22, v19
	s_nop 1
	v_add_f32_dpp v4, v4, v4 quad_perm:[2,3,0,1] row_mask:0xf bank_mask:0xf
	s_nop 1
	v_add_f32_dpp v6, v6, v6 quad_perm:[2,3,0,1] row_mask:0xf bank_mask:0xf
	s_nop 1
	v_add_f32_dpp v2, v2, v2 quad_perm:[2,3,0,1] row_mask:0xf bank_mask:0xf
	v_add_f32_e32 v19, v19, v22
	s_nop 1
	v_add_f32_dpp v4, v4, v4 row_half_mirror row_mask:0xf bank_mask:0xf
	s_nop 1
	v_add_f32_dpp v6, v6, v6 row_half_mirror row_mask:0xf bank_mask:0xf
	s_nop 1
	v_add_f32_dpp v2, v2, v2 row_half_mirror row_mask:0xf bank_mask:0xf
	s_nop 1
	v_add_f32_dpp v4, v4, v4 row_mirror row_mask:0xf bank_mask:0xf
	v_mov_b32_e32 v5, v4
	s_nop 1
	v_permlane16_swap_b32_e32 v5, v4
	v_mov_b32_e32 v20, v19
	s_nop 1
	v_permlane32_swap_b32_e32 v20, v19
	s_nop 1
	v_add_f32_dpp v6, v6, v6 row_mirror row_mask:0xf bank_mask:0xf
	s_nop 1
	v_add_f32_dpp v8, v2, v2 row_mirror row_mask:0xf bank_mask:0xf
	v_mov_b32_e32 v7, v6
	s_nop 1
	v_permlane16_swap_b32_e32 v7, v6
	v_mov_b32_e32 v9, v8
	s_nop 1
	v_permlane16_swap_b32_e32 v9, v8
	v_add_f32_e32 v2, v4, v5
	v_mov_b32_e32 v22, v21
	s_nop 1
	v_permlane32_swap_b32_e32 v22, v21
	v_mov_b32_e32 v3, v2
	s_nop 1
	v_permlane32_swap_b32_e32 v3, v2
	v_add_f32_e32 v4, v6, v7
	v_add_f32_e32 v6, v8, v9
	v_mov_b32_e32 v5, v4
	s_nop 1
	v_permlane32_swap_b32_e32 v5, v4
	v_mov_b32_e32 v7, v6
	s_nop 1
	v_permlane32_swap_b32_e32 v7, v6
	s_and_saveexec_b64 s[8:9], s[40:41]
	s_cbranch_execz .LBB0_74
	global_load_dword v8, v[72:73], off
	s_waitcnt lgkmcnt(0)
	v_add_f32_e32 v4, v4, v5
	v_add_f32_e32 v2, v2, v3
	v_add_f32_e32 v3, v21, v22
	v_add_f32_e32 v5, v19, v20
	s_ashr_i32 s5, s4, 31
	v_cndmask_b32_e64 v3, v5, v3, s[42:43]
	s_lshr_b32 s5, s5, 21
	v_cndmask_b32_e64 v2, v3, v2, s[44:45]
	v_add_f32_e32 v6, v6, v7
	s_add_i32 s5, s4, s5
	v_cndmask_b32_e64 v2, v2, v4, s[46:47]
	s_ashr_i32 s11, s5, 11
	s_and_b32 s5, s5, 0xfffff800
	v_cndmask_b32_e64 v4, v2, v6, s[48:49]
	s_sub_i32 s10, s4, s5
	v_mad_u64_u32 v[2:3], s[12:13], s11, 5, v[68:69]
	s_mov_b32 s5, 0xbfb8aa3b
	v_readlane_b32 s12, v252, 55
	v_readlane_b32 s13, v252, 56
	s_ashr_i32 s11, s10, 31
	s_waitcnt vmcnt(0)
	v_add_f32_e32 v4, v4, v8
	v_mul_f32_e64 v3, |v4|, s5
	v_exp_f32_e32 v5, v3
	s_mov_b32 s5, 0x800000
	v_ashrrev_i32_e32 v3, 31, v2
	v_lshlrev_b64 v[2:3], 13, v[2:3]
	v_add_f32_e32 v5, 1.0, v5
	v_cmp_gt_f32_e32 vcc, s5, v5
	s_mov_b32 s5, 0x3f317217
	v_lshl_add_u64 v[2:3], s[12:13], 0, v[2:3]
	v_cndmask_b32_e64 v6, 0, 32, vcc
	v_ldexp_f32 v5, v5, v6
	v_log_f32_e32 v5, v5
	v_mov_b32_e32 v6, 0x41b17218
	v_cndmask_b32_e32 v6, 0, v6, vcc
	v_min_f32_e32 v4, 0, v4
	v_mul_f32_e32 v7, 0x3f317217, v5
	v_fma_f32 v7, v5, s5, -v7
	v_fmac_f32_e32 v7, 0x3377d1cf, v5
	s_mov_b32 s5, 0x7f800000
	v_fmac_f32_e32 v7, 0x3f317217, v5
	v_cmp_lt_f32_e64 vcc, |v5|, s5
	v_lshl_add_u64 v[2:3], s[10:11], 2, v[2:3]
	s_nop 0
	v_cndmask_b32_e32 v5, v5, v7, vcc
	v_sub_f32_e32 v5, v5, v6
	v_sub_f32_e32 v4, v4, v5
	global_store_dword v[2:3], v4, off
	s_branch .LBB0_74
